# P3 weight-copy items: both gather iterations' loads issued before the first wait (loop flattened)
# speedup vs baseline: 1.0004x; 1.0004x over previous
; #define LAS __attribute__((address_space(3)))
; template <bool MAP> __device__ __forceinline__ void p0_transpose_item(const float* W, int K, int NS, bf16* WT, LAS float* scr, int item, int nkb, int lane) {
;     const int pb = item / nkb, kb = item % nkb, k0 = 64 * kb, p0 = 32 * pb;
;     const int sc = MAP ? pg8::proj_src_col(p0 + (lane & 31)) : p0 + (lane & 31);
; #pragma unroll 8
;     for (int i = 0; i < 32; ++i) { const int kk = 2 * i + (lane >> 5); scr[kk * 33 + (lane & 31)] = W[(size_t)(k0 + kk) * NS + sc]; }
.LBB0_427:
	s_lshl_b32 s64, s42, 1
	s_lshl_b32 s65, s43, 1
	v_or_b32_e32 v200, s65, v6
	s_add_i32 s66, s64, 4
	s_add_i32 s67, s65, 4
	v_mov_b32_e32 v11, v201
	s_add_i32 s69, s65, 8
	v_lshlrev_b64 v[24:25], 12, v[200:201]
	v_or_b32_e32 v10, s66, v1
	v_or_b32_e32 v200, s67, v6
	v_mov_b32_e32 v9, v201
	v_or_b32_e32 v8, s64, v1
	s_add_i32 s71, s65, 12
	v_lshlrev_b64 v[10:11], 12, v[10:11]
	v_lshlrev_b64 v[26:27], 12, v[200:201]
	v_or_b32_e32 v200, s69, v6
	s_add_i32 s68, s64, 8
	s_add_i32 s70, s64, 12
	s_add_i32 s73, s65, 16
	v_lshlrev_b64 v[8:9], 12, v[8:9]
	v_lshl_add_u64 v[24:25], v[2:3], 0, v[24:25]
	v_lshl_add_u64 v[10:11], v[2:3], 0, v[10:11]
	v_lshlrev_b64 v[28:29], 12, v[200:201]
	v_or_b32_e32 v200, s71, v6
	v_mov_b32_e32 v13, v201
	v_mov_b32_e32 v15, v201
	s_add_i32 s75, s65, 20
	v_or_b32_e32 v12, s68, v1
	v_or_b32_e32 v14, s70, v1
	v_lshl_add_u64 v[8:9], v[2:3], 0, v[8:9]
	v_lshl_add_u64 v[26:27], v[2:3], 0, v[26:27]
	global_load_dword v5, v[24:25], off
	global_load_dword v7, v[8:9], off
	global_load_dword v40, v[26:27], off
	global_load_dword v41, v[10:11], off
	v_lshlrev_b64 v[10:11], 12, v[200:201]
	v_or_b32_e32 v200, s73, v6
	s_add_i32 s72, s64, 16
	s_add_i32 s74, s64, 20
	s_add_i32 s77, s65, 24
	v_lshlrev_b64 v[12:13], 12, v[12:13]
	v_lshlrev_b64 v[14:15], 12, v[14:15]
	v_lshl_add_u64 v[8:9], v[2:3], 0, v[28:29]
	v_lshl_add_u64 v[10:11], v[2:3], 0, v[10:11]
	v_lshlrev_b64 v[24:25], 12, v[200:201]
	v_or_b32_e32 v200, s75, v6
	v_mov_b32_e32 v17, v201
	v_mov_b32_e32 v19, v201
	s_add_i32 s76, s64, 24
	s_add_i32 s78, s64, 28
	s_add_i32 s79, s65, 28
	v_or_b32_e32 v16, s72, v1
	v_or_b32_e32 v18, s74, v1
	v_lshl_add_u64 v[12:13], v[2:3], 0, v[12:13]
	v_lshl_add_u64 v[14:15], v[2:3], 0, v[14:15]
	global_load_dword v42, v[8:9], off
	global_load_dword v43, v[12:13], off
	global_load_dword v44, v[10:11], off
	global_load_dword v45, v[14:15], off
	v_lshlrev_b64 v[10:11], 12, v[200:201]
	v_or_b32_e32 v200, s77, v6
	v_mov_b32_e32 v21, v201
	v_mov_b32_e32 v23, v201
	v_or_b32_e32 v20, s76, v1
	v_or_b32_e32 v22, s78, v1
	v_lshlrev_b64 v[16:17], 12, v[16:17]
	v_lshlrev_b64 v[18:19], 12, v[18:19]
	v_lshl_add_u64 v[8:9], v[2:3], 0, v[24:25]
	v_lshl_add_u64 v[10:11], v[2:3], 0, v[10:11]
	v_lshlrev_b64 v[12:13], 12, v[200:201]
	v_or_b32_e32 v200, s79, v6
	v_lshlrev_b64 v[20:21], 12, v[20:21]
	v_lshlrev_b64 v[22:23], 12, v[22:23]
	v_lshl_add_u64 v[16:17], v[2:3], 0, v[16:17]
	v_lshl_add_u64 v[18:19], v[2:3], 0, v[18:19]
	global_load_dword v46, v[8:9], off
	global_load_dword v47, v[16:17], off
	global_load_dword v48, v[10:11], off
	global_load_dword v49, v[18:19], off
	v_lshl_add_u64 v[8:9], v[2:3], 0, v[12:13]
	v_lshlrev_b64 v[10:11], 12, v[200:201]
	v_lshl_add_u64 v[20:21], v[2:3], 0, v[20:21]
	v_lshl_add_u64 v[22:23], v[2:3], 0, v[22:23]
	v_lshl_add_u64 v[10:11], v[2:3], 0, v[10:11]
	global_load_dword v50, v[8:9], off
	global_load_dword v51, v[20:21], off
	global_load_dword v52, v[10:11], off
	global_load_dword v53, v[22:23], off
	v_or_b32_e32 v10, s64, v199
	v_or_b32_e32 v8, s65, v198
	s_add_i32 s43, s43, 16
	s_add_i32 s42, s42, 16
	s_add_i32 s63, s63, -16
	v_or_b32_e32 v18, s68, v199
	v_or_b32_e32 v16, s69, v198
	v_or_b32_e32 v22, s70, v199
	v_or_b32_e32 v20, s71, v198
	v_or_b32_e32 v26, s72, v199
	v_or_b32_e32 v24, s73, v198
	v_or_b32_e32 v30, s74, v199
	v_or_b32_e32 v28, s75, v198
	v_or_b32_e32 v34, s76, v199
	v_or_b32_e32 v32, s77, v198
	v_or_b32_e32 v38, s78, v199
	v_or_b32_e32 v36, s79, v198
	s_cmp_lg_u32 s63, 0
	v_mad_u64_u32 v[8:9], s[64:65], v8, s46, v[4:5]
	v_mad_u64_u32 v[10:11], s[64:65], v10, s46, v[4:5]
	v_or_b32_e32 v9, s66, v199
	v_or_b32_e32 v11, s67, v198
	v_mad_u64_u32 v[12:13], s[64:65], v11, s46, v[4:5]
	v_mad_u64_u32 v[14:15], s[64:65], v9, s46, v[4:5]
	v_mad_u64_u32 v[16:17], s[64:65], v16, s46, v[4:5]
	v_mad_u64_u32 v[18:19], s[64:65], v18, s46, v[4:5]
	v_mad_u64_u32 v[20:21], s[64:65], v20, s46, v[4:5]
	v_mad_u64_u32 v[22:23], s[64:65], v22, s46, v[4:5]
	v_mad_u64_u32 v[24:25], s[64:65], v24, s46, v[4:5]
	v_mad_u64_u32 v[26:27], s[64:65], v26, s46, v[4:5]
	v_mad_u64_u32 v[28:29], s[64:65], v28, s46, v[4:5]
	v_mad_u64_u32 v[30:31], s[64:65], v30, s46, v[4:5]
	v_mad_u64_u32 v[32:33], s[64:65], v32, s46, v[4:5]
	v_mad_u64_u32 v[34:35], s[64:65], v34, s46, v[4:5]
	v_mad_u64_u32 v[36:37], s[64:65], v36, s46, v[4:5]
	v_mad_u64_u32 v[38:39], s[64:65], v38, s46, v[4:5]
	s_lshl_b32 s64, s42, 1
	s_lshl_b32 s65, s43, 1
	v_or_b32_e32 v200, s65, v6
	s_add_i32 s66, s64, 4
	s_add_i32 s67, s65, 4
	v_mov_b32_e32 v67, v201
	s_add_i32 s69, s65, 8
	v_lshlrev_b64 v[80:81], 12, v[200:201]
	v_or_b32_e32 v66, s66, v1
	v_or_b32_e32 v200, s67, v6
	v_mov_b32_e32 v65, v201
	v_or_b32_e32 v64, s64, v1
	s_add_i32 s71, s65, 12
	v_lshlrev_b64 v[66:67], 12, v[66:67]
	v_lshlrev_b64 v[82:83], 12, v[200:201]
	v_or_b32_e32 v200, s69, v6
	s_add_i32 s68, s64, 8
	s_add_i32 s70, s64, 12
	s_add_i32 s73, s65, 16
	v_lshlrev_b64 v[64:65], 12, v[64:65]
	v_lshl_add_u64 v[80:81], v[2:3], 0, v[80:81]
	v_lshl_add_u64 v[66:67], v[2:3], 0, v[66:67]
	v_lshlrev_b64 v[84:85], 12, v[200:201]
	v_or_b32_e32 v200, s71, v6
	v_mov_b32_e32 v69, v201
	v_mov_b32_e32 v71, v201
	s_add_i32 s75, s65, 20
	v_or_b32_e32 v68, s68, v1
	v_or_b32_e32 v70, s70, v1
	v_lshl_add_u64 v[64:65], v[2:3], 0, v[64:65]
	v_lshl_add_u64 v[82:83], v[2:3], 0, v[82:83]
	global_load_dword v61, v[80:81], off
	global_load_dword v63, v[64:65], off
	global_load_dword v96, v[82:83], off
	global_load_dword v97, v[66:67], off
	v_lshlrev_b64 v[66:67], 12, v[200:201]
	v_or_b32_e32 v200, s73, v6
	s_add_i32 s72, s64, 16
	s_add_i32 s74, s64, 20
	s_add_i32 s77, s65, 24
	v_lshlrev_b64 v[68:69], 12, v[68:69]
; template <bool MAP> __device__ __forceinline__ void p0_transpose_item(const float* W, int K, int NS, bf16* WT, LAS float* scr, int item, int nkb, int lane) {
;     ...
;     for (int i = 0; i < 32; ++i) { const int kk = 2 * i + (lane >> 5); scr[kk * 33 + (lane & 31)] = W[(size_t)(k0 + kk) * NS + sc]; }
	v_lshlrev_b64 v[70:71], 12, v[70:71]
	v_lshl_add_u64 v[64:65], v[2:3], 0, v[84:85]
	v_lshl_add_u64 v[66:67], v[2:3], 0, v[66:67]
	v_lshlrev_b64 v[80:81], 12, v[200:201]
	v_or_b32_e32 v200, s75, v6
	v_mov_b32_e32 v73, v201
	v_mov_b32_e32 v75, v201
	s_add_i32 s76, s64, 24
	s_add_i32 s78, s64, 28
	s_add_i32 s79, s65, 28
	v_or_b32_e32 v72, s72, v1
	v_or_b32_e32 v74, s74, v1
	v_lshl_add_u64 v[68:69], v[2:3], 0, v[68:69]
	v_lshl_add_u64 v[70:71], v[2:3], 0, v[70:71]
	global_load_dword v98, v[64:65], off
	global_load_dword v99, v[68:69], off
	global_load_dword v100, v[66:67], off
	global_load_dword v101, v[70:71], off
	v_lshlrev_b64 v[66:67], 12, v[200:201]
	v_or_b32_e32 v200, s77, v6
	v_mov_b32_e32 v77, v201
	v_mov_b32_e32 v79, v201
	v_or_b32_e32 v76, s76, v1
	v_or_b32_e32 v78, s78, v1
	v_lshlrev_b64 v[72:73], 12, v[72:73]
	v_lshlrev_b64 v[74:75], 12, v[74:75]
	v_lshl_add_u64 v[64:65], v[2:3], 0, v[80:81]
	v_lshl_add_u64 v[66:67], v[2:3], 0, v[66:67]
	v_lshlrev_b64 v[68:69], 12, v[200:201]
	v_or_b32_e32 v200, s79, v6
	v_lshlrev_b64 v[76:77], 12, v[76:77]
	v_lshlrev_b64 v[78:79], 12, v[78:79]
	v_lshl_add_u64 v[72:73], v[2:3], 0, v[72:73]
	v_lshl_add_u64 v[74:75], v[2:3], 0, v[74:75]
	global_load_dword v102, v[64:65], off
	global_load_dword v103, v[72:73], off
	global_load_dword v104, v[66:67], off
	global_load_dword v105, v[74:75], off
	v_lshl_add_u64 v[64:65], v[2:3], 0, v[68:69]
	v_lshlrev_b64 v[66:67], 12, v[200:201]
	v_lshl_add_u64 v[76:77], v[2:3], 0, v[76:77]
	v_lshl_add_u64 v[78:79], v[2:3], 0, v[78:79]
	v_lshl_add_u64 v[66:67], v[2:3], 0, v[66:67]
	global_load_dword v106, v[64:65], off
	global_load_dword v107, v[76:77], off
	global_load_dword v108, v[66:67], off
	global_load_dword v109, v[78:79], off
	s_waitcnt vmcnt(31)
	ds_write_b32 v8, v5
	s_waitcnt vmcnt(30)
	ds_write_b32 v10, v7
	s_waitcnt vmcnt(29)
	ds_write_b32 v12, v40
	s_waitcnt vmcnt(28)
	ds_write_b32 v14, v41
	s_waitcnt vmcnt(27)
	ds_write_b32 v16, v42
	s_waitcnt vmcnt(26)
	ds_write_b32 v18, v43
	s_waitcnt vmcnt(25)
	ds_write_b32 v20, v44
	s_waitcnt vmcnt(24)
	ds_write_b32 v22, v45
	s_waitcnt vmcnt(23)
	ds_write_b32 v24, v46
	s_waitcnt vmcnt(22)
	ds_write_b32 v26, v47
	s_waitcnt vmcnt(21)
	ds_write_b32 v28, v48
	s_waitcnt vmcnt(20)
	ds_write_b32 v30, v49
	s_waitcnt vmcnt(19)
	ds_write_b32 v32, v50
	s_waitcnt vmcnt(18)
	ds_write_b32 v34, v51
	s_waitcnt vmcnt(17)
	ds_write_b32 v36, v52
	s_waitcnt vmcnt(16)
	ds_write_b32 v38, v53
	v_or_b32_e32 v10, s64, v199
	v_or_b32_e32 v8, s65, v198
	s_add_i32 s43, s43, 16
	s_add_i32 s42, s42, 16
	s_add_i32 s63, s63, -16
	v_or_b32_e32 v18, s68, v199
	v_or_b32_e32 v16, s69, v198
	v_or_b32_e32 v22, s70, v199
	v_or_b32_e32 v20, s71, v198
	v_or_b32_e32 v26, s72, v199
	v_or_b32_e32 v24, s73, v198
	v_or_b32_e32 v30, s74, v199
	v_or_b32_e32 v28, s75, v198
	v_or_b32_e32 v34, s76, v199
	v_or_b32_e32 v32, s77, v198
	v_or_b32_e32 v38, s78, v199
	v_or_b32_e32 v36, s79, v198
	s_cmp_lg_u32 s63, 0
	v_mad_u64_u32 v[8:9], s[64:65], v8, s46, v[4:5]
	v_mad_u64_u32 v[10:11], s[64:65], v10, s46, v[4:5]
	v_or_b32_e32 v9, s66, v199
	v_or_b32_e32 v11, s67, v198
	v_mad_u64_u32 v[12:13], s[64:65], v11, s46, v[4:5]
	v_mad_u64_u32 v[14:15], s[64:65], v9, s46, v[4:5]
	v_mad_u64_u32 v[16:17], s[64:65], v16, s46, v[4:5]
	v_mad_u64_u32 v[18:19], s[64:65], v18, s46, v[4:5]
	v_mad_u64_u32 v[20:21], s[64:65], v20, s46, v[4:5]
	v_mad_u64_u32 v[22:23], s[64:65], v22, s46, v[4:5]
	v_mad_u64_u32 v[24:25], s[64:65], v24, s46, v[4:5]
	v_mad_u64_u32 v[26:27], s[64:65], v26, s46, v[4:5]
	v_mad_u64_u32 v[28:29], s[64:65], v28, s46, v[4:5]
	v_mad_u64_u32 v[30:31], s[64:65], v30, s46, v[4:5]
	v_mad_u64_u32 v[32:33], s[64:65], v32, s46, v[4:5]
	v_mad_u64_u32 v[34:35], s[64:65], v34, s46, v[4:5]
	v_mad_u64_u32 v[36:37], s[64:65], v36, s46, v[4:5]
	v_mad_u64_u32 v[38:39], s[64:65], v38, s46, v[4:5]
	s_waitcnt vmcnt(15)
; #define GAS __attribute__((address_space(1)))
; #define LAS __attribute__((address_space(3)))
; #define LDS_WAIT() asm volatile("s_waitcnt lgkmcnt(0)" ::: "memory")
; __device__ __forceinline__ unsigned pk2(float lo, float hi) { return pg8::cvt_pk_bf16(lo, hi); }
; template <bool MAP> __device__ __forceinline__ void p0_transpose_item(const float* W, int K, int NS, bf16* WT, LAS float* scr, int item, int nkb, int lane) {
;     ...
;     for (int i = 0; i < 32; ++i) { const int kk = 2 * i + (lane >> 5); scr[kk * 33 + (lane & 31)] = W[(size_t)(k0 + kk) * NS + sc]; }
;     LDS_WAIT(); asm volatile("" ::: "memory");
;     const int c = lane & 7;
; #pragma unroll
;     for (int j = 0; j < 4; ++j) { const int n = (lane >> 3) + 8 * j; const LAS float* s = scr + (8 * c) * 33 + n;
;         v4u o; o.x = pk2(s[0 * 33], s[1 * 33]); o.y = pk2(s[2 * 33], s[3 * 33]); o.z = pk2(s[4 * 33], s[5 * 33]); o.w = pk2(s[6 * 33], s[7 * 33]);
;         *(GAS v4u*)(WT + (size_t)(p0 + n) * K + k0 + 8 * c) = o; }
;     LDS_WAIT(); asm volatile("" ::: "memory");
	ds_write_b32 v8, v61
	s_waitcnt vmcnt(14)
	ds_write_b32 v10, v63
	s_waitcnt vmcnt(13)
	ds_write_b32 v12, v96
	s_waitcnt vmcnt(12)
	ds_write_b32 v14, v97
	s_waitcnt vmcnt(11)
	ds_write_b32 v16, v98
	s_waitcnt vmcnt(10)
	ds_write_b32 v18, v99
	s_waitcnt vmcnt(9)
	ds_write_b32 v20, v100
	s_waitcnt vmcnt(8)
	ds_write_b32 v22, v101
	s_waitcnt vmcnt(7)
	ds_write_b32 v24, v102
	s_waitcnt vmcnt(6)
	ds_write_b32 v26, v103
	s_waitcnt vmcnt(5)
	ds_write_b32 v28, v104
	s_waitcnt vmcnt(4)
	ds_write_b32 v30, v105
	s_waitcnt vmcnt(3)
	ds_write_b32 v32, v106
	s_waitcnt vmcnt(2)
	ds_write_b32 v34, v107
	s_waitcnt vmcnt(1)
	ds_write_b32 v36, v108
	s_waitcnt vmcnt(0)
	ds_write_b32 v38, v109
	s_lshl_b32 s41, s41, 1
	s_waitcnt lgkmcnt(0)
	v_lshlrev_b32_e32 v1, 2, v233
	v_mul_u32_u24_e32 v2, 0x84, v204
	s_add_u32 s42, s6, s41
	v_add3_u32 v1, s12, v2, v1
	v_lshlrev_b32_e32 v200, 1, v204
	s_addc_u32 s43, s7, 0
	ds_read2_b32 v[2:3], v1 offset1:33
	v_lshl_add_u64 v[8:9], s[42:43], 0, v[200:201]
	v_or_b32_e32 v200, s40, v233
	s_waitcnt lgkmcnt(0)
	v_cvt_pk_bf16_f32 v2, v2, v3
	ds_read2_b32 v[4:5], v1 offset0:66 offset1:99
	v_lshl_add_u64 v[8:9], v[8:9], 0, s[34:35]
	v_lshlrev_b64 v[10:11], 11, v[200:201]
	s_waitcnt lgkmcnt(0)
	v_cvt_pk_bf16_f32 v3, v4, v5
	ds_read2_b32 v[4:5], v1 offset0:132 offset1:165
	v_lshl_add_u64 v[10:11], v[8:9], 0, v[10:11]
	s_waitcnt lgkmcnt(0)
	v_cvt_pk_bf16_f32 v4, v4, v5
	ds_read2_b32 v[6:7], v1 offset0:198 offset1:231
	s_waitcnt lgkmcnt(0)
	v_cvt_pk_bf16_f32 v5, v6, v7
	global_store_dwordx4 v[10:11], v[2:5], off
	v_or_b32_e32 v10, 8, v233
	v_or_b32_e32 v200, s40, v10
	ds_read2_b32 v[6:7], v1 offset0:8 offset1:41
	s_waitcnt lgkmcnt(0)
	v_cvt_pk_bf16_f32 v2, v6, v7
	ds_read2_b32 v[4:5], v1 offset0:74 offset1:107
	v_lshlrev_b64 v[10:11], 11, v[200:201]
	s_waitcnt lgkmcnt(0)
	v_cvt_pk_bf16_f32 v3, v4, v5
	ds_read2_b32 v[4:5], v1 offset0:140 offset1:173
	v_lshl_add_u64 v[10:11], v[8:9], 0, v[10:11]
	s_waitcnt lgkmcnt(0)
	v_cvt_pk_bf16_f32 v4, v4, v5
	ds_read2_b32 v[6:7], v1 offset0:206 offset1:239
	s_waitcnt lgkmcnt(0)
	v_cvt_pk_bf16_f32 v5, v6, v7
	global_store_dwordx4 v[10:11], v[2:5], off
	v_or_b32_e32 v10, 16, v233
	ds_read2_b32 v[6:7], v1 offset0:16 offset1:49
	s_waitcnt lgkmcnt(0)
	v_cvt_pk_bf16_f32 v2, v6, v7
	ds_read2_b32 v[4:5], v1 offset0:82 offset1:115
	v_or_b32_e32 v200, s40, v10
	s_waitcnt lgkmcnt(0)
	v_cvt_pk_bf16_f32 v3, v4, v5
	ds_read2_b32 v[4:5], v1 offset0:148 offset1:181
	v_lshlrev_b64 v[10:11], 11, v[200:201]
	s_waitcnt lgkmcnt(0)
	v_cvt_pk_bf16_f32 v4, v4, v5
	ds_read2_b32 v[6:7], v1 offset0:214 offset1:247
	s_waitcnt lgkmcnt(0)
	v_cvt_pk_bf16_f32 v5, v6, v7
	v_lshl_add_u64 v[10:11], v[8:9], 0, v[10:11]
	ds_read2_b32 v[6:7], v1 offset0:24 offset1:57
	global_store_dwordx4 v[10:11], v[2:5], off
	s_mov_b64 s[42:43], 0
	s_waitcnt lgkmcnt(0)
	v_cvt_pk_bf16_f32 v2, v6, v7
	ds_read2_b32 v[4:5], v1 offset0:90 offset1:123
	s_waitcnt lgkmcnt(0)
	v_cvt_pk_bf16_f32 v3, v4, v5
	ds_read2_b32 v[4:5], v1 offset0:156 offset1:189
	s_waitcnt lgkmcnt(0)
	v_cvt_pk_bf16_f32 v4, v4, v5
	ds_read2_b32 v[6:7], v1 offset0:222 offset1:255
	v_or_b32_e32 v1, 24, v233
	v_or_b32_e32 v200, s40, v1
	v_lshlrev_b64 v[10:11], 11, v[200:201]
	s_waitcnt lgkmcnt(0)
	v_cvt_pk_bf16_f32 v5, v6, v7
	v_lshl_add_u64 v[6:7], v[8:9], 0, v[10:11]
	global_store_dwordx4 v[6:7], v[2:5], off
	s_waitcnt lgkmcnt(0)

; #define LAS __attribute__((address_space(3)))
; template <bool MAP> __device__ __forceinline__ void p0_transpose_item(const float* W, int K, int NS, bf16* WT, LAS float* scr, int item, int nkb, int lane) {
;     const int pb = item / nkb, kb = item % nkb, k0 = 64 * kb, p0 = 32 * pb;
;     const int sc = MAP ? pg8::proj_src_col(p0 + (lane & 31)) : p0 + (lane & 31);
; #pragma unroll 8
;     for (int i = 0; i < 32; ++i) { const int kk = 2 * i + (lane >> 5); scr[kk * 33 + (lane & 31)] = W[(size_t)(k0 + kk) * NS + sc]; }
.LBB0_431:
	s_lshl_b32 s43, s10, 1
	s_lshl_b32 s63, s11, 1
	v_or_b32_e32 v200, s63, v6
	s_add_i32 s66, s43, 4
	s_add_i32 s67, s63, 4
	v_mov_b32_e32 v11, v201
	s_add_i32 s69, s63, 8
	v_lshlrev_b64 v[24:25], 12, v[200:201]
	v_or_b32_e32 v10, s66, v1
	v_or_b32_e32 v200, s67, v6
	v_mov_b32_e32 v9, v201
	v_or_b32_e32 v8, s43, v1
	s_add_i32 s71, s63, 12
	v_lshlrev_b64 v[10:11], 12, v[10:11]
	v_lshlrev_b64 v[26:27], 12, v[200:201]
	v_or_b32_e32 v200, s69, v6
	s_add_i32 s68, s43, 8
	s_add_i32 s70, s43, 12
	s_add_i32 s73, s63, 16
	v_lshlrev_b64 v[8:9], 12, v[8:9]
	v_lshl_add_u64 v[24:25], v[2:3], 0, v[24:25]
	v_lshl_add_u64 v[10:11], v[2:3], 0, v[10:11]
	v_lshlrev_b64 v[28:29], 12, v[200:201]
	v_or_b32_e32 v200, s71, v6
	v_mov_b32_e32 v13, v201
	v_mov_b32_e32 v15, v201
	s_add_i32 s75, s63, 20
	v_or_b32_e32 v12, s68, v1
	v_or_b32_e32 v14, s70, v1
	v_lshl_add_u64 v[8:9], v[2:3], 0, v[8:9]
	v_lshl_add_u64 v[26:27], v[2:3], 0, v[26:27]
	global_load_dword v5, v[24:25], off
	global_load_dword v7, v[8:9], off
	global_load_dword v40, v[26:27], off
	global_load_dword v41, v[10:11], off
	v_lshlrev_b64 v[10:11], 12, v[200:201]
	v_or_b32_e32 v200, s73, v6
	s_add_i32 s72, s43, 16
	s_add_i32 s74, s43, 20
	s_add_i32 s77, s63, 24
	v_lshlrev_b64 v[12:13], 12, v[12:13]
	v_lshlrev_b64 v[14:15], 12, v[14:15]
	v_lshl_add_u64 v[8:9], v[2:3], 0, v[28:29]
	v_lshl_add_u64 v[10:11], v[2:3], 0, v[10:11]
	v_lshlrev_b64 v[24:25], 12, v[200:201]
	v_or_b32_e32 v200, s75, v6
	v_mov_b32_e32 v17, v201
	v_mov_b32_e32 v19, v201
	s_add_i32 s76, s43, 24
	s_add_i32 s78, s43, 28
	s_add_i32 s79, s63, 28
	v_or_b32_e32 v16, s72, v1
	v_or_b32_e32 v18, s74, v1
	v_lshl_add_u64 v[12:13], v[2:3], 0, v[12:13]
	v_lshl_add_u64 v[14:15], v[2:3], 0, v[14:15]
	global_load_dword v42, v[8:9], off
	global_load_dword v43, v[12:13], off
	global_load_dword v44, v[10:11], off
	global_load_dword v45, v[14:15], off
	v_lshlrev_b64 v[10:11], 12, v[200:201]
	v_or_b32_e32 v200, s77, v6
	v_mov_b32_e32 v21, v201
	v_mov_b32_e32 v23, v201
	v_or_b32_e32 v20, s76, v1
	v_or_b32_e32 v22, s78, v1
	v_lshlrev_b64 v[16:17], 12, v[16:17]
	v_lshlrev_b64 v[18:19], 12, v[18:19]
	v_lshl_add_u64 v[8:9], v[2:3], 0, v[24:25]
	v_lshl_add_u64 v[10:11], v[2:3], 0, v[10:11]
	v_lshlrev_b64 v[12:13], 12, v[200:201]
	v_or_b32_e32 v200, s79, v6
	v_lshlrev_b64 v[20:21], 12, v[20:21]
	v_lshlrev_b64 v[22:23], 12, v[22:23]
	v_lshl_add_u64 v[16:17], v[2:3], 0, v[16:17]
	v_lshl_add_u64 v[18:19], v[2:3], 0, v[18:19]
	global_load_dword v46, v[8:9], off
	global_load_dword v47, v[16:17], off
	global_load_dword v48, v[10:11], off
	global_load_dword v49, v[18:19], off
	v_lshl_add_u64 v[8:9], v[2:3], 0, v[12:13]
	v_lshlrev_b64 v[10:11], 12, v[200:201]
	v_lshl_add_u64 v[20:21], v[2:3], 0, v[20:21]
	v_lshl_add_u64 v[22:23], v[2:3], 0, v[22:23]
	v_lshl_add_u64 v[10:11], v[2:3], 0, v[10:11]
	global_load_dword v50, v[8:9], off
	global_load_dword v51, v[20:21], off
	global_load_dword v52, v[10:11], off
	global_load_dword v53, v[22:23], off
	v_or_b32_e32 v10, s43, v199
	v_or_b32_e32 v8, s63, v198
	s_add_i32 s11, s11, 16
	s_add_i32 s10, s10, 16
	s_add_i32 s42, s42, -16
	v_or_b32_e32 v18, s68, v199
	v_or_b32_e32 v16, s69, v198
	v_or_b32_e32 v22, s70, v199
	v_or_b32_e32 v20, s71, v198
	v_or_b32_e32 v26, s72, v199
	v_or_b32_e32 v24, s73, v198
	v_or_b32_e32 v30, s74, v199
	v_or_b32_e32 v28, s75, v198
	v_or_b32_e32 v34, s76, v199
	v_or_b32_e32 v32, s77, v198
	v_or_b32_e32 v38, s78, v199
	v_or_b32_e32 v36, s79, v198
	s_cmp_lg_u32 s42, 0
	v_mad_u64_u32 v[8:9], s[64:65], v8, s46, v[4:5]
	v_mad_u64_u32 v[10:11], s[64:65], v10, s46, v[4:5]
	v_or_b32_e32 v9, s66, v199
	v_or_b32_e32 v11, s67, v198
	v_mad_u64_u32 v[12:13], s[64:65], v11, s46, v[4:5]
	v_mad_u64_u32 v[14:15], s[64:65], v9, s46, v[4:5]
	v_mad_u64_u32 v[16:17], s[64:65], v16, s46, v[4:5]
	v_mad_u64_u32 v[18:19], s[64:65], v18, s46, v[4:5]
	v_mad_u64_u32 v[20:21], s[64:65], v20, s46, v[4:5]
	v_mad_u64_u32 v[22:23], s[64:65], v22, s46, v[4:5]
	v_mad_u64_u32 v[24:25], s[64:65], v24, s46, v[4:5]
	v_mad_u64_u32 v[26:27], s[64:65], v26, s46, v[4:5]
	v_mad_u64_u32 v[28:29], s[64:65], v28, s46, v[4:5]
	v_mad_u64_u32 v[30:31], s[64:65], v30, s46, v[4:5]
	v_mad_u64_u32 v[32:33], s[64:65], v32, s46, v[4:5]
	v_mad_u64_u32 v[34:35], s[64:65], v34, s46, v[4:5]
	v_mad_u64_u32 v[36:37], s[64:65], v36, s46, v[4:5]
	v_mad_u64_u32 v[38:39], s[64:65], v38, s46, v[4:5]
	s_lshl_b32 s43, s10, 1
	s_lshl_b32 s63, s11, 1
	v_or_b32_e32 v200, s63, v6
	s_add_i32 s66, s43, 4
	s_add_i32 s67, s63, 4
	v_mov_b32_e32 v67, v201
	s_add_i32 s69, s63, 8
	v_lshlrev_b64 v[80:81], 12, v[200:201]
	v_or_b32_e32 v66, s66, v1
	v_or_b32_e32 v200, s67, v6
	v_mov_b32_e32 v65, v201
	v_or_b32_e32 v64, s43, v1
	s_add_i32 s71, s63, 12
	v_lshlrev_b64 v[66:67], 12, v[66:67]
	v_lshlrev_b64 v[82:83], 12, v[200:201]
	v_or_b32_e32 v200, s69, v6
	s_add_i32 s68, s43, 8
	s_add_i32 s70, s43, 12
	s_add_i32 s73, s63, 16
	v_lshlrev_b64 v[64:65], 12, v[64:65]
	v_lshl_add_u64 v[80:81], v[2:3], 0, v[80:81]
	v_lshl_add_u64 v[66:67], v[2:3], 0, v[66:67]
	v_lshlrev_b64 v[84:85], 12, v[200:201]
	v_or_b32_e32 v200, s71, v6
	v_mov_b32_e32 v69, v201
	v_mov_b32_e32 v71, v201
	s_add_i32 s75, s63, 20
	v_or_b32_e32 v68, s68, v1
	v_or_b32_e32 v70, s70, v1
	v_lshl_add_u64 v[64:65], v[2:3], 0, v[64:65]
	v_lshl_add_u64 v[82:83], v[2:3], 0, v[82:83]
	global_load_dword v61, v[80:81], off
	global_load_dword v63, v[64:65], off
	global_load_dword v96, v[82:83], off
	global_load_dword v97, v[66:67], off
	v_lshlrev_b64 v[66:67], 12, v[200:201]
	v_or_b32_e32 v200, s73, v6
	s_add_i32 s72, s43, 16
	s_add_i32 s74, s43, 20
	s_add_i32 s77, s63, 24
	v_lshlrev_b64 v[68:69], 12, v[68:69]
; template <bool MAP> __device__ __forceinline__ void p0_transpose_item(const float* W, int K, int NS, bf16* WT, LAS float* scr, int item, int nkb, int lane) {
;     ...
;     for (int i = 0; i < 32; ++i) { const int kk = 2 * i + (lane >> 5); scr[kk * 33 + (lane & 31)] = W[(size_t)(k0 + kk) * NS + sc]; }
	v_lshlrev_b64 v[70:71], 12, v[70:71]
	v_lshl_add_u64 v[64:65], v[2:3], 0, v[84:85]
	v_lshl_add_u64 v[66:67], v[2:3], 0, v[66:67]
	v_lshlrev_b64 v[80:81], 12, v[200:201]
	v_or_b32_e32 v200, s75, v6
	v_mov_b32_e32 v73, v201
	v_mov_b32_e32 v75, v201
	s_add_i32 s76, s43, 24
	s_add_i32 s78, s43, 28
	s_add_i32 s79, s63, 28
	v_or_b32_e32 v72, s72, v1
	v_or_b32_e32 v74, s74, v1
	v_lshl_add_u64 v[68:69], v[2:3], 0, v[68:69]
	v_lshl_add_u64 v[70:71], v[2:3], 0, v[70:71]
	global_load_dword v98, v[64:65], off
	global_load_dword v99, v[68:69], off
	global_load_dword v100, v[66:67], off
	global_load_dword v101, v[70:71], off
	v_lshlrev_b64 v[66:67], 12, v[200:201]
	v_or_b32_e32 v200, s77, v6
	v_mov_b32_e32 v77, v201
	v_mov_b32_e32 v79, v201
	v_or_b32_e32 v76, s76, v1
	v_or_b32_e32 v78, s78, v1
	v_lshlrev_b64 v[72:73], 12, v[72:73]
	v_lshlrev_b64 v[74:75], 12, v[74:75]
	v_lshl_add_u64 v[64:65], v[2:3], 0, v[80:81]
	v_lshl_add_u64 v[66:67], v[2:3], 0, v[66:67]
	v_lshlrev_b64 v[68:69], 12, v[200:201]
	v_or_b32_e32 v200, s79, v6
	v_lshlrev_b64 v[76:77], 12, v[76:77]
	v_lshlrev_b64 v[78:79], 12, v[78:79]
	v_lshl_add_u64 v[72:73], v[2:3], 0, v[72:73]
	v_lshl_add_u64 v[74:75], v[2:3], 0, v[74:75]
	global_load_dword v102, v[64:65], off
	global_load_dword v103, v[72:73], off
	global_load_dword v104, v[66:67], off
	global_load_dword v105, v[74:75], off
	v_lshl_add_u64 v[64:65], v[2:3], 0, v[68:69]
	v_lshlrev_b64 v[66:67], 12, v[200:201]
	v_lshl_add_u64 v[76:77], v[2:3], 0, v[76:77]
	v_lshl_add_u64 v[78:79], v[2:3], 0, v[78:79]
	v_lshl_add_u64 v[66:67], v[2:3], 0, v[66:67]
	global_load_dword v106, v[64:65], off
	global_load_dword v107, v[76:77], off
	global_load_dword v108, v[66:67], off
	global_load_dword v109, v[78:79], off
	s_waitcnt vmcnt(31)
	ds_write_b32 v8, v5
	s_waitcnt vmcnt(30)
	ds_write_b32 v10, v7
	s_waitcnt vmcnt(29)
	ds_write_b32 v12, v40
	s_waitcnt vmcnt(28)
	ds_write_b32 v14, v41
	s_waitcnt vmcnt(27)
	ds_write_b32 v16, v42
	s_waitcnt vmcnt(26)
	ds_write_b32 v18, v43
	s_waitcnt vmcnt(25)
	ds_write_b32 v20, v44
	s_waitcnt vmcnt(24)
	ds_write_b32 v22, v45
	s_waitcnt vmcnt(23)
	ds_write_b32 v24, v46
	s_waitcnt vmcnt(22)
	ds_write_b32 v26, v47
	s_waitcnt vmcnt(21)
	ds_write_b32 v28, v48
	s_waitcnt vmcnt(20)
	ds_write_b32 v30, v49
	s_waitcnt vmcnt(19)
	ds_write_b32 v32, v50
	s_waitcnt vmcnt(18)
	ds_write_b32 v34, v51
	s_waitcnt vmcnt(17)
	ds_write_b32 v36, v52
	s_waitcnt vmcnt(16)
	ds_write_b32 v38, v53
	v_or_b32_e32 v10, s43, v199
	v_or_b32_e32 v8, s63, v198
	s_add_i32 s11, s11, 16
	s_add_i32 s10, s10, 16
	s_add_i32 s42, s42, -16
	v_or_b32_e32 v18, s68, v199
	v_or_b32_e32 v16, s69, v198
	v_or_b32_e32 v22, s70, v199
	v_or_b32_e32 v20, s71, v198
	v_or_b32_e32 v26, s72, v199
	v_or_b32_e32 v24, s73, v198
	v_or_b32_e32 v30, s74, v199
	v_or_b32_e32 v28, s75, v198
	v_or_b32_e32 v34, s76, v199
	v_or_b32_e32 v32, s77, v198
	v_or_b32_e32 v38, s78, v199
	v_or_b32_e32 v36, s79, v198
	s_cmp_lg_u32 s42, 0
	v_mad_u64_u32 v[8:9], s[64:65], v8, s46, v[4:5]
	v_mad_u64_u32 v[10:11], s[64:65], v10, s46, v[4:5]
	v_or_b32_e32 v9, s66, v199
	v_or_b32_e32 v11, s67, v198
	v_mad_u64_u32 v[12:13], s[64:65], v11, s46, v[4:5]
	v_mad_u64_u32 v[14:15], s[64:65], v9, s46, v[4:5]
	v_mad_u64_u32 v[16:17], s[64:65], v16, s46, v[4:5]
	v_mad_u64_u32 v[18:19], s[64:65], v18, s46, v[4:5]
	v_mad_u64_u32 v[20:21], s[64:65], v20, s46, v[4:5]
	v_mad_u64_u32 v[22:23], s[64:65], v22, s46, v[4:5]
	v_mad_u64_u32 v[24:25], s[64:65], v24, s46, v[4:5]
	v_mad_u64_u32 v[26:27], s[64:65], v26, s46, v[4:5]
	v_mad_u64_u32 v[28:29], s[64:65], v28, s46, v[4:5]
	v_mad_u64_u32 v[30:31], s[64:65], v30, s46, v[4:5]
	v_mad_u64_u32 v[32:33], s[64:65], v32, s46, v[4:5]
	v_mad_u64_u32 v[34:35], s[64:65], v34, s46, v[4:5]
	v_mad_u64_u32 v[36:37], s[64:65], v36, s46, v[4:5]
	v_mad_u64_u32 v[38:39], s[64:65], v38, s46, v[4:5]
	s_waitcnt vmcnt(15)
; #define GAS __attribute__((address_space(1)))
; #define LAS __attribute__((address_space(3)))
; #define LDS_WAIT() asm volatile("s_waitcnt lgkmcnt(0)" ::: "memory")
; __device__ __forceinline__ unsigned pk2(float lo, float hi) { return pg8::cvt_pk_bf16(lo, hi); }
; template <bool MAP> __device__ __forceinline__ void p0_transpose_item(const float* W, int K, int NS, bf16* WT, LAS float* scr, int item, int nkb, int lane) {
;     ...
;     for (int i = 0; i < 32; ++i) { const int kk = 2 * i + (lane >> 5); scr[kk * 33 + (lane & 31)] = W[(size_t)(k0 + kk) * NS + sc]; }
;     LDS_WAIT(); asm volatile("" ::: "memory");
;     const int c = lane & 7;
; #pragma unroll
;     for (int j = 0; j < 4; ++j) { const int n = (lane >> 3) + 8 * j; const LAS float* s = scr + (8 * c) * 33 + n;
;         v4u o; o.x = pk2(s[0 * 33], s[1 * 33]); o.y = pk2(s[2 * 33], s[3 * 33]); o.z = pk2(s[4 * 33], s[5 * 33]); o.w = pk2(s[6 * 33], s[7 * 33]);
;         *(GAS v4u*)(WT + (size_t)(p0 + n) * K + k0 + 8 * c) = o; }
;     LDS_WAIT(); asm volatile("" ::: "memory");
	ds_write_b32 v8, v61
	s_waitcnt vmcnt(14)
	ds_write_b32 v10, v63
	s_waitcnt vmcnt(13)
	ds_write_b32 v12, v96
	s_waitcnt vmcnt(12)
	ds_write_b32 v14, v97
	s_waitcnt vmcnt(11)
	ds_write_b32 v16, v98
	s_waitcnt vmcnt(10)
	ds_write_b32 v18, v99
	s_waitcnt vmcnt(9)
	ds_write_b32 v20, v100
	s_waitcnt vmcnt(8)
	ds_write_b32 v22, v101
	s_waitcnt vmcnt(7)
	ds_write_b32 v24, v102
	s_waitcnt vmcnt(6)
	ds_write_b32 v26, v103
	s_waitcnt vmcnt(5)
	ds_write_b32 v28, v104
	s_waitcnt vmcnt(4)
	ds_write_b32 v30, v105
	s_waitcnt vmcnt(3)
	ds_write_b32 v32, v106
	s_waitcnt vmcnt(2)
	ds_write_b32 v34, v107
	s_waitcnt vmcnt(1)
	ds_write_b32 v36, v108
	s_waitcnt vmcnt(0)
	ds_write_b32 v38, v109
	s_lshl_b32 s10, s41, 1
	s_waitcnt lgkmcnt(0)
	v_lshlrev_b32_e32 v1, 2, v233
	v_mul_u32_u24_e32 v2, 0x84, v204
	s_add_u32 s10, s6, s10
	v_add3_u32 v1, s12, v2, v1
	v_lshlrev_b32_e32 v200, 1, v204
	s_addc_u32 s11, s7, 0
	ds_read2_b32 v[2:3], v1 offset1:33
	v_or_b32_e32 v10, s40, v233
	v_lshl_add_u64 v[8:9], s[10:11], 0, v[200:201]
	s_waitcnt lgkmcnt(0)
	v_cvt_pk_bf16_f32 v2, v2, v3
	ds_read2_b32 v[4:5], v1 offset0:66 offset1:99
	v_lshlrev_b32_e32 v200, 11, v10
	v_lshl_add_u64 v[8:9], v[8:9], 0, s[36:37]
	s_waitcnt lgkmcnt(0)
	v_cvt_pk_bf16_f32 v3, v4, v5
	ds_read2_b32 v[4:5], v1 offset0:132 offset1:165
	v_lshl_add_u64 v[10:11], v[8:9], 0, v[200:201]
	s_waitcnt lgkmcnt(0)
	v_cvt_pk_bf16_f32 v4, v4, v5
	ds_read2_b32 v[6:7], v1 offset0:198 offset1:231
	s_waitcnt lgkmcnt(0)
	v_cvt_pk_bf16_f32 v5, v6, v7
	global_store_dwordx4 v[10:11], v[2:5], off
	v_or_b32_e32 v10, 8, v233
	v_or_b32_e32 v10, s40, v10
	ds_read2_b32 v[6:7], v1 offset0:8 offset1:41
	s_waitcnt lgkmcnt(0)
	v_cvt_pk_bf16_f32 v2, v6, v7
	ds_read2_b32 v[4:5], v1 offset0:74 offset1:107
	v_lshlrev_b32_e32 v200, 11, v10
	s_waitcnt lgkmcnt(0)
	v_cvt_pk_bf16_f32 v3, v4, v5
	ds_read2_b32 v[4:5], v1 offset0:140 offset1:173
	v_lshl_add_u64 v[10:11], v[8:9], 0, v[200:201]
	s_waitcnt lgkmcnt(0)
	v_cvt_pk_bf16_f32 v4, v4, v5
	ds_read2_b32 v[6:7], v1 offset0:206 offset1:239
	s_waitcnt lgkmcnt(0)
	v_cvt_pk_bf16_f32 v5, v6, v7
	global_store_dwordx4 v[10:11], v[2:5], off
	v_or_b32_e32 v10, 16, v233
	ds_read2_b32 v[6:7], v1 offset0:16 offset1:49
	s_waitcnt lgkmcnt(0)
	v_cvt_pk_bf16_f32 v2, v6, v7
	ds_read2_b32 v[4:5], v1 offset0:82 offset1:115
	v_or_b32_e32 v10, s40, v10
	s_waitcnt lgkmcnt(0)
	v_cvt_pk_bf16_f32 v3, v4, v5
	ds_read2_b32 v[4:5], v1 offset0:148 offset1:181
	v_lshlrev_b32_e32 v200, 11, v10
	s_waitcnt lgkmcnt(0)
	v_cvt_pk_bf16_f32 v4, v4, v5
	ds_read2_b32 v[6:7], v1 offset0:214 offset1:247
	s_waitcnt lgkmcnt(0)
	v_cvt_pk_bf16_f32 v5, v6, v7
	v_lshl_add_u64 v[10:11], v[8:9], 0, v[200:201]
	ds_read2_b32 v[6:7], v1 offset0:24 offset1:57
	global_store_dwordx4 v[10:11], v[2:5], off
	s_waitcnt lgkmcnt(0)
	s_nop 0
	v_cvt_pk_bf16_f32 v2, v6, v7
	ds_read2_b32 v[4:5], v1 offset0:90 offset1:123
	s_waitcnt lgkmcnt(0)
	v_cvt_pk_bf16_f32 v3, v4, v5
	ds_read2_b32 v[4:5], v1 offset0:156 offset1:189
	s_waitcnt lgkmcnt(0)
	v_cvt_pk_bf16_f32 v4, v4, v5
	ds_read2_b32 v[6:7], v1 offset0:222 offset1:255
	v_or_b32_e32 v1, 24, v233
	v_or_b32_e32 v1, s40, v1
	v_lshlrev_b32_e32 v200, 11, v1
	s_waitcnt lgkmcnt(0)
	v_cvt_pk_bf16_f32 v5, v6, v7
	v_lshl_add_u64 v[6:7], v[8:9], 0, v[200:201]
	global_store_dwordx4 v[6:7], v[2:5], off
	s_waitcnt lgkmcnt(0)

; #define LAS __attribute__((address_space(3)))
; template <bool MAP> __device__ __forceinline__ void p0_transpose_item(const float* W, int K, int NS, bf16* WT, LAS float* scr, int item, int nkb, int lane) {
;     const int pb = item / nkb, kb = item % nkb, k0 = 64 * kb, p0 = 32 * pb;
;     const int sc = MAP ? pg8::proj_src_col(p0 + (lane & 31)) : p0 + (lane & 31);
; #pragma unroll 8
;     for (int i = 0; i < 32; ++i) { const int kk = 2 * i + (lane >> 5); scr[kk * 33 + (lane & 31)] = W[(size_t)(k0 + kk) * NS + sc]; }
.LBB0_436:
	s_lshl_b32 s41, s8, 1
	s_lshl_b32 s42, s9, 1
	v_or_b32_e32 v200, s42, v6
	s_add_i32 s44, s41, 4
	s_add_i32 s45, s42, 4
	v_mov_b32_e32 v11, v201
	s_add_i32 s64, s42, 8
	v_lshlrev_b64 v[24:25], 12, v[200:201]
	v_or_b32_e32 v10, s44, v1
	v_or_b32_e32 v200, s45, v6
	v_mov_b32_e32 v9, v201
	v_or_b32_e32 v8, s41, v1
	s_add_i32 s66, s42, 12
	v_lshlrev_b64 v[10:11], 12, v[10:11]
	v_lshlrev_b64 v[26:27], 12, v[200:201]
	v_or_b32_e32 v200, s64, v6
	s_add_i32 s63, s41, 8
	s_add_i32 s65, s41, 12
	s_add_i32 s68, s42, 16
	v_lshlrev_b64 v[8:9], 12, v[8:9]
	v_lshl_add_u64 v[24:25], v[2:3], 0, v[24:25]
	v_lshl_add_u64 v[10:11], v[2:3], 0, v[10:11]
	v_lshlrev_b64 v[28:29], 12, v[200:201]
	v_or_b32_e32 v200, s66, v6
	v_mov_b32_e32 v13, v201
	v_mov_b32_e32 v15, v201
	s_add_i32 s70, s42, 20
	v_or_b32_e32 v12, s63, v1
	v_or_b32_e32 v14, s65, v1
	v_lshl_add_u64 v[8:9], v[2:3], 0, v[8:9]
	v_lshl_add_u64 v[26:27], v[2:3], 0, v[26:27]
	global_load_dword v5, v[24:25], off
	global_load_dword v7, v[8:9], off
	global_load_dword v40, v[26:27], off
	global_load_dword v41, v[10:11], off
	v_lshlrev_b64 v[10:11], 12, v[200:201]
	v_or_b32_e32 v200, s68, v6
	s_add_i32 s67, s41, 16
	s_add_i32 s69, s41, 20
	s_add_i32 s72, s42, 24
	v_lshlrev_b64 v[12:13], 12, v[12:13]
	v_lshlrev_b64 v[14:15], 12, v[14:15]
	v_lshl_add_u64 v[8:9], v[2:3], 0, v[28:29]
	v_lshl_add_u64 v[10:11], v[2:3], 0, v[10:11]
	v_lshlrev_b64 v[24:25], 12, v[200:201]
	v_or_b32_e32 v200, s70, v6
	v_mov_b32_e32 v17, v201
	v_mov_b32_e32 v19, v201
	s_add_i32 s71, s41, 24
	s_add_i32 s73, s41, 28
	s_add_i32 s74, s42, 28
	v_or_b32_e32 v16, s67, v1
	v_or_b32_e32 v18, s69, v1
	v_lshl_add_u64 v[12:13], v[2:3], 0, v[12:13]
	v_lshl_add_u64 v[14:15], v[2:3], 0, v[14:15]
	global_load_dword v42, v[8:9], off
	global_load_dword v43, v[12:13], off
	global_load_dword v44, v[10:11], off
	global_load_dword v45, v[14:15], off
	v_lshlrev_b64 v[10:11], 12, v[200:201]
	v_or_b32_e32 v200, s72, v6
	v_mov_b32_e32 v21, v201
	v_mov_b32_e32 v23, v201
	v_or_b32_e32 v20, s71, v1
	v_or_b32_e32 v22, s73, v1
	v_lshlrev_b64 v[16:17], 12, v[16:17]
	v_lshlrev_b64 v[18:19], 12, v[18:19]
	v_lshl_add_u64 v[8:9], v[2:3], 0, v[24:25]
	v_lshl_add_u64 v[10:11], v[2:3], 0, v[10:11]
	v_lshlrev_b64 v[12:13], 12, v[200:201]
	v_or_b32_e32 v200, s74, v6
	v_lshlrev_b64 v[20:21], 12, v[20:21]
	v_lshlrev_b64 v[22:23], 12, v[22:23]
	v_lshl_add_u64 v[16:17], v[2:3], 0, v[16:17]
	v_lshl_add_u64 v[18:19], v[2:3], 0, v[18:19]
	global_load_dword v46, v[8:9], off
	global_load_dword v47, v[16:17], off
	global_load_dword v48, v[10:11], off
	global_load_dword v49, v[18:19], off
	v_lshl_add_u64 v[8:9], v[2:3], 0, v[12:13]
	v_lshlrev_b64 v[10:11], 12, v[200:201]
	v_lshl_add_u64 v[20:21], v[2:3], 0, v[20:21]
	v_lshl_add_u64 v[22:23], v[2:3], 0, v[22:23]
	v_lshl_add_u64 v[10:11], v[2:3], 0, v[10:11]
	global_load_dword v50, v[8:9], off
	global_load_dword v51, v[20:21], off
	global_load_dword v52, v[10:11], off
	global_load_dword v53, v[22:23], off
	v_or_b32_e32 v10, s41, v199
	v_or_b32_e32 v8, s42, v198
	s_add_i32 s9, s9, 16
	s_add_i32 s8, s8, 16
	s_add_i32 s40, s40, -16
	v_or_b32_e32 v18, s63, v199
	v_or_b32_e32 v16, s64, v198
	v_or_b32_e32 v22, s65, v199
	v_or_b32_e32 v20, s66, v198
	v_or_b32_e32 v26, s67, v199
	v_or_b32_e32 v24, s68, v198
	v_or_b32_e32 v30, s69, v199
	v_or_b32_e32 v28, s70, v198
	v_or_b32_e32 v34, s71, v199
	v_or_b32_e32 v32, s72, v198
	v_or_b32_e32 v38, s73, v199
	v_or_b32_e32 v36, s74, v198
	s_cmp_lg_u32 s40, 0
	v_mad_u64_u32 v[8:9], s[42:43], v8, s46, v[4:5]
	v_mad_u64_u32 v[10:11], s[42:43], v10, s46, v[4:5]
	v_or_b32_e32 v9, s44, v199
	v_or_b32_e32 v11, s45, v198
	v_mad_u64_u32 v[12:13], s[42:43], v11, s46, v[4:5]
	v_mad_u64_u32 v[14:15], s[42:43], v9, s46, v[4:5]
	v_mad_u64_u32 v[16:17], s[42:43], v16, s46, v[4:5]
	v_mad_u64_u32 v[18:19], s[42:43], v18, s46, v[4:5]
	v_mad_u64_u32 v[20:21], s[42:43], v20, s46, v[4:5]
	v_mad_u64_u32 v[22:23], s[42:43], v22, s46, v[4:5]
	v_mad_u64_u32 v[24:25], s[42:43], v24, s46, v[4:5]
	v_mad_u64_u32 v[26:27], s[42:43], v26, s46, v[4:5]
	v_mad_u64_u32 v[28:29], s[42:43], v28, s46, v[4:5]
	v_mad_u64_u32 v[30:31], s[42:43], v30, s46, v[4:5]
	v_mad_u64_u32 v[32:33], s[42:43], v32, s46, v[4:5]
	v_mad_u64_u32 v[34:35], s[42:43], v34, s46, v[4:5]
	v_mad_u64_u32 v[36:37], s[42:43], v36, s46, v[4:5]
	v_mad_u64_u32 v[38:39], s[42:43], v38, s46, v[4:5]
	s_lshl_b32 s41, s8, 1
	s_lshl_b32 s42, s9, 1
	v_or_b32_e32 v200, s42, v6
	s_add_i32 s44, s41, 4
	s_add_i32 s45, s42, 4
	v_mov_b32_e32 v67, v201
	s_add_i32 s64, s42, 8
	v_lshlrev_b64 v[80:81], 12, v[200:201]
	v_or_b32_e32 v66, s44, v1
	v_or_b32_e32 v200, s45, v6
	v_mov_b32_e32 v65, v201
	v_or_b32_e32 v64, s41, v1
	s_add_i32 s66, s42, 12
	v_lshlrev_b64 v[66:67], 12, v[66:67]
	v_lshlrev_b64 v[82:83], 12, v[200:201]
	v_or_b32_e32 v200, s64, v6
	s_add_i32 s63, s41, 8
	s_add_i32 s65, s41, 12
	s_add_i32 s68, s42, 16
	v_lshlrev_b64 v[64:65], 12, v[64:65]
	v_lshl_add_u64 v[80:81], v[2:3], 0, v[80:81]
	v_lshl_add_u64 v[66:67], v[2:3], 0, v[66:67]
	v_lshlrev_b64 v[84:85], 12, v[200:201]
	v_or_b32_e32 v200, s66, v6
	v_mov_b32_e32 v69, v201
	v_mov_b32_e32 v71, v201
	s_add_i32 s70, s42, 20
	v_or_b32_e32 v68, s63, v1
	v_or_b32_e32 v70, s65, v1
	v_lshl_add_u64 v[64:65], v[2:3], 0, v[64:65]
	v_lshl_add_u64 v[82:83], v[2:3], 0, v[82:83]
	global_load_dword v61, v[80:81], off
	global_load_dword v63, v[64:65], off
	global_load_dword v96, v[82:83], off
	global_load_dword v97, v[66:67], off
	v_lshlrev_b64 v[66:67], 12, v[200:201]
	v_or_b32_e32 v200, s68, v6
	s_add_i32 s67, s41, 16
	s_add_i32 s69, s41, 20
	s_add_i32 s72, s42, 24
	v_lshlrev_b64 v[68:69], 12, v[68:69]
	v_lshlrev_b64 v[70:71], 12, v[70:71]
; template <bool MAP> __device__ __forceinline__ void p0_transpose_item(const float* W, int K, int NS, bf16* WT, LAS float* scr, int item, int nkb, int lane) {
;     ...
;     for (int i = 0; i < 32; ++i) { const int kk = 2 * i + (lane >> 5); scr[kk * 33 + (lane & 31)] = W[(size_t)(k0 + kk) * NS + sc]; }
	v_lshl_add_u64 v[64:65], v[2:3], 0, v[84:85]
	v_lshl_add_u64 v[66:67], v[2:3], 0, v[66:67]
	v_lshlrev_b64 v[80:81], 12, v[200:201]
	v_or_b32_e32 v200, s70, v6
	v_mov_b32_e32 v73, v201
	v_mov_b32_e32 v75, v201
	s_add_i32 s71, s41, 24
	s_add_i32 s73, s41, 28
	s_add_i32 s74, s42, 28
	v_or_b32_e32 v72, s67, v1
	v_or_b32_e32 v74, s69, v1
	v_lshl_add_u64 v[68:69], v[2:3], 0, v[68:69]
	v_lshl_add_u64 v[70:71], v[2:3], 0, v[70:71]
	global_load_dword v98, v[64:65], off
	global_load_dword v99, v[68:69], off
	global_load_dword v100, v[66:67], off
	global_load_dword v101, v[70:71], off
	v_lshlrev_b64 v[66:67], 12, v[200:201]
	v_or_b32_e32 v200, s72, v6
	v_mov_b32_e32 v77, v201
	v_mov_b32_e32 v79, v201
	v_or_b32_e32 v76, s71, v1
	v_or_b32_e32 v78, s73, v1
	v_lshlrev_b64 v[72:73], 12, v[72:73]
	v_lshlrev_b64 v[74:75], 12, v[74:75]
	v_lshl_add_u64 v[64:65], v[2:3], 0, v[80:81]
	v_lshl_add_u64 v[66:67], v[2:3], 0, v[66:67]
	v_lshlrev_b64 v[68:69], 12, v[200:201]
	v_or_b32_e32 v200, s74, v6
	v_lshlrev_b64 v[76:77], 12, v[76:77]
	v_lshlrev_b64 v[78:79], 12, v[78:79]
	v_lshl_add_u64 v[72:73], v[2:3], 0, v[72:73]
	v_lshl_add_u64 v[74:75], v[2:3], 0, v[74:75]
	global_load_dword v102, v[64:65], off
	global_load_dword v103, v[72:73], off
	global_load_dword v104, v[66:67], off
	global_load_dword v105, v[74:75], off
	v_lshl_add_u64 v[64:65], v[2:3], 0, v[68:69]
	v_lshlrev_b64 v[66:67], 12, v[200:201]
	v_lshl_add_u64 v[76:77], v[2:3], 0, v[76:77]
	v_lshl_add_u64 v[78:79], v[2:3], 0, v[78:79]
	v_lshl_add_u64 v[66:67], v[2:3], 0, v[66:67]
	global_load_dword v106, v[64:65], off
	global_load_dword v107, v[76:77], off
	global_load_dword v108, v[66:67], off
	global_load_dword v109, v[78:79], off
	s_waitcnt vmcnt(31)
	ds_write_b32 v8, v5
	s_waitcnt vmcnt(30)
	ds_write_b32 v10, v7
	s_waitcnt vmcnt(29)
	ds_write_b32 v12, v40
	s_waitcnt vmcnt(28)
	ds_write_b32 v14, v41
	s_waitcnt vmcnt(27)
	ds_write_b32 v16, v42
	s_waitcnt vmcnt(26)
	ds_write_b32 v18, v43
	s_waitcnt vmcnt(25)
	ds_write_b32 v20, v44
	s_waitcnt vmcnt(24)
	ds_write_b32 v22, v45
	s_waitcnt vmcnt(23)
	ds_write_b32 v24, v46
	s_waitcnt vmcnt(22)
	ds_write_b32 v26, v47
	s_waitcnt vmcnt(21)
	ds_write_b32 v28, v48
	s_waitcnt vmcnt(20)
	ds_write_b32 v30, v49
	s_waitcnt vmcnt(19)
	ds_write_b32 v32, v50
	s_waitcnt vmcnt(18)
	ds_write_b32 v34, v51
	s_waitcnt vmcnt(17)
	ds_write_b32 v36, v52
	s_waitcnt vmcnt(16)
	ds_write_b32 v38, v53
	v_or_b32_e32 v10, s41, v199
	v_or_b32_e32 v8, s42, v198
	s_add_i32 s9, s9, 16
	s_add_i32 s8, s8, 16
	s_add_i32 s40, s40, -16
	v_or_b32_e32 v18, s63, v199
	v_or_b32_e32 v16, s64, v198
	v_or_b32_e32 v22, s65, v199
	v_or_b32_e32 v20, s66, v198
	v_or_b32_e32 v26, s67, v199
	v_or_b32_e32 v24, s68, v198
	v_or_b32_e32 v30, s69, v199
	v_or_b32_e32 v28, s70, v198
	v_or_b32_e32 v34, s71, v199
	v_or_b32_e32 v32, s72, v198
	v_or_b32_e32 v38, s73, v199
	v_or_b32_e32 v36, s74, v198
	s_cmp_lg_u32 s40, 0
	v_mad_u64_u32 v[8:9], s[42:43], v8, s46, v[4:5]
	v_mad_u64_u32 v[10:11], s[42:43], v10, s46, v[4:5]
	v_or_b32_e32 v9, s44, v199
	v_or_b32_e32 v11, s45, v198
	v_mad_u64_u32 v[12:13], s[42:43], v11, s46, v[4:5]
	v_mad_u64_u32 v[14:15], s[42:43], v9, s46, v[4:5]
	v_mad_u64_u32 v[16:17], s[42:43], v16, s46, v[4:5]
	v_mad_u64_u32 v[18:19], s[42:43], v18, s46, v[4:5]
	v_mad_u64_u32 v[20:21], s[42:43], v20, s46, v[4:5]
	v_mad_u64_u32 v[22:23], s[42:43], v22, s46, v[4:5]
	v_mad_u64_u32 v[24:25], s[42:43], v24, s46, v[4:5]
	v_mad_u64_u32 v[26:27], s[42:43], v26, s46, v[4:5]
	v_mad_u64_u32 v[28:29], s[42:43], v28, s46, v[4:5]
	v_mad_u64_u32 v[30:31], s[42:43], v30, s46, v[4:5]
	v_mad_u64_u32 v[32:33], s[42:43], v32, s46, v[4:5]
	v_mad_u64_u32 v[34:35], s[42:43], v34, s46, v[4:5]
	v_mad_u64_u32 v[36:37], s[42:43], v36, s46, v[4:5]
	v_mad_u64_u32 v[38:39], s[42:43], v38, s46, v[4:5]
	s_waitcnt vmcnt(15)
; #define GAS __attribute__((address_space(1)))
; #define LAS __attribute__((address_space(3)))
; #define LDS_WAIT() asm volatile("s_waitcnt lgkmcnt(0)" ::: "memory")
; __device__ __forceinline__ unsigned pk2(float lo, float hi) { return pg8::cvt_pk_bf16(lo, hi); }
; template <bool MAP> __device__ __forceinline__ void p0_transpose_item(const float* W, int K, int NS, bf16* WT, LAS float* scr, int item, int nkb, int lane) {
;     ...
;     for (int i = 0; i < 32; ++i) { const int kk = 2 * i + (lane >> 5); scr[kk * 33 + (lane & 31)] = W[(size_t)(k0 + kk) * NS + sc]; }
;     LDS_WAIT(); asm volatile("" ::: "memory");
;     const int c = lane & 7;
; #pragma unroll
;     for (int j = 0; j < 4; ++j) { const int n = (lane >> 3) + 8 * j; const LAS float* s = scr + (8 * c) * 33 + n;
;         v4u o; o.x = pk2(s[0 * 33], s[1 * 33]); o.y = pk2(s[2 * 33], s[3 * 33]); o.z = pk2(s[4 * 33], s[5 * 33]); o.w = pk2(s[6 * 33], s[7 * 33]);
;         *(GAS v4u*)(WT + (size_t)(p0 + n) * K + k0 + 8 * c) = o; }
;     LDS_WAIT(); asm volatile("" ::: "memory");
	ds_write_b32 v8, v61
	s_waitcnt vmcnt(14)
	ds_write_b32 v10, v63
	s_waitcnt vmcnt(13)
	ds_write_b32 v12, v96
	s_waitcnt vmcnt(12)
	ds_write_b32 v14, v97
	s_waitcnt vmcnt(11)
	ds_write_b32 v16, v98
	s_waitcnt vmcnt(10)
	ds_write_b32 v18, v99
	s_waitcnt vmcnt(9)
	ds_write_b32 v20, v100
	s_waitcnt vmcnt(8)
	ds_write_b32 v22, v101
	s_waitcnt vmcnt(7)
	ds_write_b32 v24, v102
	s_waitcnt vmcnt(6)
	ds_write_b32 v26, v103
	s_waitcnt vmcnt(5)
	ds_write_b32 v28, v104
	s_waitcnt vmcnt(4)
	ds_write_b32 v30, v105
	s_waitcnt vmcnt(3)
	ds_write_b32 v32, v106
	s_waitcnt vmcnt(2)
	ds_write_b32 v34, v107
	s_waitcnt vmcnt(1)
	ds_write_b32 v36, v108
	s_waitcnt vmcnt(0)
	ds_write_b32 v38, v109
	s_lshl_b32 s8, s11, 1
	s_waitcnt lgkmcnt(0)
	v_lshlrev_b32_e32 v1, 2, v233
	v_mul_u32_u24_e32 v2, 0x84, v204
	s_add_u32 s6, s6, s8
	v_add3_u32 v1, s12, v2, v1
	v_lshlrev_b32_e32 v200, 1, v204
	s_addc_u32 s7, s7, 0
	ds_read2_b32 v[2:3], v1 offset1:33
	v_or_b32_e32 v10, s10, v233
	v_lshl_add_u64 v[8:9], s[6:7], 0, v[200:201]
	s_waitcnt lgkmcnt(0)
	v_cvt_pk_bf16_f32 v2, v2, v3
	ds_read2_b32 v[4:5], v1 offset0:66 offset1:99
	v_lshlrev_b32_e32 v200, 11, v10
	v_lshl_add_u64 v[8:9], v[8:9], 0, s[38:39]
	s_waitcnt lgkmcnt(0)
	v_cvt_pk_bf16_f32 v3, v4, v5
	ds_read2_b32 v[4:5], v1 offset0:132 offset1:165
	v_lshl_add_u64 v[10:11], v[8:9], 0, v[200:201]
	s_waitcnt lgkmcnt(0)
	v_cvt_pk_bf16_f32 v4, v4, v5
	ds_read2_b32 v[6:7], v1 offset0:198 offset1:231
	s_waitcnt lgkmcnt(0)
	v_cvt_pk_bf16_f32 v5, v6, v7
	global_store_dwordx4 v[10:11], v[2:5], off
	v_or_b32_e32 v10, 8, v233
	v_or_b32_e32 v10, s10, v10
	ds_read2_b32 v[6:7], v1 offset0:8 offset1:41
	s_waitcnt lgkmcnt(0)
	v_cvt_pk_bf16_f32 v2, v6, v7
	ds_read2_b32 v[4:5], v1 offset0:74 offset1:107
	v_lshlrev_b32_e32 v200, 11, v10
	s_waitcnt lgkmcnt(0)
	v_cvt_pk_bf16_f32 v3, v4, v5
	ds_read2_b32 v[4:5], v1 offset0:140 offset1:173
	v_lshl_add_u64 v[10:11], v[8:9], 0, v[200:201]
	s_waitcnt lgkmcnt(0)
	v_cvt_pk_bf16_f32 v4, v4, v5
	ds_read2_b32 v[6:7], v1 offset0:206 offset1:239
	s_waitcnt lgkmcnt(0)
	v_cvt_pk_bf16_f32 v5, v6, v7
	global_store_dwordx4 v[10:11], v[2:5], off
	v_or_b32_e32 v10, 16, v233
	ds_read2_b32 v[6:7], v1 offset0:16 offset1:49
	s_waitcnt lgkmcnt(0)
	v_cvt_pk_bf16_f32 v2, v6, v7
	ds_read2_b32 v[4:5], v1 offset0:82 offset1:115
	v_or_b32_e32 v10, s10, v10
	s_waitcnt lgkmcnt(0)
	v_cvt_pk_bf16_f32 v3, v4, v5
	ds_read2_b32 v[4:5], v1 offset0:148 offset1:181
	v_lshlrev_b32_e32 v200, 11, v10
	s_waitcnt lgkmcnt(0)
	v_cvt_pk_bf16_f32 v4, v4, v5
	ds_read2_b32 v[6:7], v1 offset0:214 offset1:247
	s_waitcnt lgkmcnt(0)
	v_cvt_pk_bf16_f32 v5, v6, v7
	v_lshl_add_u64 v[10:11], v[8:9], 0, v[200:201]
	ds_read2_b32 v[6:7], v1 offset0:24 offset1:57
	global_store_dwordx4 v[10:11], v[2:5], off
	s_waitcnt lgkmcnt(0)
	s_nop 0
	v_cvt_pk_bf16_f32 v2, v6, v7
	ds_read2_b32 v[4:5], v1 offset0:90 offset1:123
	s_waitcnt lgkmcnt(0)
	v_cvt_pk_bf16_f32 v3, v4, v5
	ds_read2_b32 v[4:5], v1 offset0:156 offset1:189
	s_waitcnt lgkmcnt(0)
	v_cvt_pk_bf16_f32 v4, v4, v5
	ds_read2_b32 v[6:7], v1 offset0:222 offset1:255
	v_or_b32_e32 v1, 24, v233
	v_or_b32_e32 v1, s10, v1
	v_lshlrev_b32_e32 v200, 11, v1
	s_waitcnt lgkmcnt(0)
	v_cvt_pk_bf16_f32 v5, v6, v7
	v_lshl_add_u64 v[6:7], v[8:9], 0, v[200:201]
	global_store_dwordx4 v[6:7], v[2:5], off
	s_waitcnt lgkmcnt(0)
	s_branch .LBB0_340
